# experiment on combo: wave 1 of every workgroup issues an early L2 write-back (buffer_wbl2 sc1, not waited) on arrival at each grid barrier
# baseline (speedup 1.0000x reference)
.LBB0_1041:
	s_cmp_lg_u32 s1, s68
	s_mov_b64 s[4:5], -1
	s_cbranch_scc0 .LBB0_1095
	s_waitcnt vmcnt(0)
	v_cmp_eq_u32_e32 vcc, 0, v186
	s_waitcnt vmcnt(0) lgkmcnt(0)
	s_barrier
	v_readfirstlane_b32 s0, v186
	s_cmp_eq_u32 s0, 64
	s_cbranch_scc0 .Lbar_noflush
	s_mov_b64 s[0:1], exec
	s_mov_b64 exec, 1
	buffer_wbl2 sc1
	s_mov_b64 exec, s[0:1]
.Lbar_noflush:
	s_and_saveexec_b64 s[6:7], vcc
	s_cbranch_execz .LBB0_1094
	v_readlane_b32 s1, v255, 12
	s_waitcnt vmcnt(0) expcnt(0) lgkmcnt(0)
	s_getreg_b32 s0, hwreg(HW_REG_XCC_ID, 0, 4)
	v_mov_b32_e32 v4, s1
	ds_read_b32 v6, v4
	v_readlane_b32 s1, v255, 13
	s_and_b32 s0, s0, 15
	s_waitcnt lgkmcnt(0)
	v_cmp_ne_u32_e32 vcc, 0, v6
	v_mov_b32_e32 v4, s1
	ds_read_b32 v4, v4
	s_cbranch_vccnz .LBB0_1058
	s_add_u32 s8, s78, 0x1f885200
	s_addc_u32 s9, s79, 0
	s_add_u32 s10, s78, 0x1f885400
	s_addc_u32 s11, s79, 0
	s_add_u32 s12, s78, 0x1f885500
	s_addc_u32 s13, s79, 0
	s_add_u32 s14, s78, 0x1f885600
	s_addc_u32 s15, s79, 0
	s_add_u32 s16, s78, 0x1f885700
	s_addc_u32 s17, s79, 0
	s_add_u32 s18, s78, 0x1f885800
	s_addc_u32 s19, s79, 0
	s_add_u32 s20, s78, 0x1f885900
	s_addc_u32 s21, s79, 0
	s_add_u32 s22, s78, 0x1f885a00
	s_addc_u32 s23, s79, 0
	s_add_u32 s24, s78, 0x1f885b00
	s_addc_u32 s25, s79, 0
	s_add_u32 s26, s78, 0x1f885c00
	s_addc_u32 s27, s79, 0
	s_add_u32 s28, s78, 0x1f885d00
	s_addc_u32 s29, s79, 0
	s_add_u32 s30, s78, 0x1f885e00
	s_addc_u32 s31, s79, 0
	s_add_u32 s34, s78, 0x1f885f00
	s_addc_u32 s35, s79, 0
	s_add_u32 s36, s78, 0x1f886000
	s_addc_u32 s37, s79, 0
	s_add_u32 s38, s78, 0x1f886100
	s_addc_u32 s39, s79, 0
	s_add_u32 s40, s78, 0x1f886200
	s_addc_u32 s41, s79, 0
	s_add_u32 s42, s78, 0x1f886300
	s_addc_u32 s43, s79, 0
	s_mov_b32 s1, 1
	s_branch .LBB0_1046
